# speedup vs baseline: 1.0044x; 1.0044x over previous
; #define LDSP(TY, p) ((__attribute__((address_space(3))) TY*)(p))
; #define WAIT_L0() asm volatile("s_waitcnt lgkmcnt(0)" ::: "memory")
; __device__ __forceinline__ void ph_attn(const Params& p, char* shm) {
;     ...
;     s16x8 qb[16];
;     const u16* qp = p.QLAT + (size_t)r * 8192 + hd * 512 + g4 * 8;
; #pragma unroll
;     for (int ks = 0; ks < 16; ++ks) qb[ks] = *(const s16x8*)(qp + ks * 32);
;     f32x4 O[32];
; #pragma unroll
;     for (int dt = 0; dt < 32; ++dt) O[dt] = f32x4{0.f, 0.f, 0.f, 0.f};
;     float mref = -INFINITY, lsum = 0.f;
;     for (int c = 0; c < nchunk; ++c) {
;       const int slot = c * 16 + hd;
;       int iv = (slot < cnt) ? slot : 0;
;       if (t >= 256) iv = idxl[slot];
;       WAIT_L0();
; #pragma unroll
;       for (int j = 0; j < 16; ++j) {
;         const int kidx = __builtin_amdgcn_readlane(iv, j);
;         __builtin_amdgcn_global_load_lds((const unsigned*)(ckvb + (size_t)kidx * 512 + lane * 8), LDSP(unsigned, wb + j * 1040), 16, 0, 0);
;     ...
;       float pj[4];
; #pragma unroll
;       for (int j = 0; j < 4; ++j) { pj[j] = __expf(sv[j] - mref); lsum += pj[j]; }
;       const s16x4 pb = {(short)f2bf(pj[0]), (short)f2bf(pj[1]), (short)f2bf(pj[2]), (short)f2bf(pj[3])};
; #pragma unroll
.LBB0_902:
	v_readlane_b32 s6, v244, 0
	v_readlane_b32 s7, v244, 1
	s_lshl_b64 s[0:1], s[6:7], 14
	v_lshl_add_u64 v[0:1], v[196:197], 0, s[0:1]
	global_load_dwordx4 v[132:135], v[0:1], off
	global_load_dwordx4 v[136:139], v[0:1], off offset:64
	global_load_dwordx4 v[140:143], v[0:1], off offset:128
	global_load_dwordx4 v[144:147], v[0:1], off offset:192
	global_load_dwordx4 v[148:151], v[0:1], off offset:256
	global_load_dwordx4 v[152:155], v[0:1], off offset:320
	global_load_dwordx4 v[156:159], v[0:1], off offset:384
	global_load_dwordx4 v[160:163], v[0:1], off offset:448
	global_load_dwordx4 v[164:167], v[0:1], off offset:512
	global_load_dwordx4 v[168:171], v[0:1], off offset:576
	global_load_dwordx4 v[172:175], v[0:1], off offset:640
	global_load_dwordx4 v[176:179], v[0:1], off offset:704
	global_load_dwordx4 v[180:183], v[0:1], off offset:768
	global_load_dwordx4 v[184:187], v[0:1], off offset:832
	global_load_dwordx4 v[188:191], v[0:1], off offset:896
	global_load_dwordx4 v[192:195], v[0:1], off offset:960
	s_ashr_i32 s0, s6, 13
	s_min_u32 s4, s15, 0xff
	s_ashr_i32 s1, s0, 31
	v_mov_b32_e32 v32, v33
	v_mov_b32_e32 v34, v33
	v_mov_b32_e32 v35, v33
	s_add_i32 s15, s4, 16
	s_lshl_b64 s[0:1], s[0:1], 23
	v_mov_b64_e32 v[24:25], v[32:33]
	v_mov_b64_e32 v[38:39], v[34:35]
	v_mov_b64_e32 v[46:47], v[34:35]
	v_mov_b64_e32 v[50:51], v[34:35]
	v_mov_b64_e32 v[54:55], v[34:35]
	v_mov_b64_e32 v[58:59], v[34:35]
	v_mov_b64_e32 v[62:63], v[34:35]
	v_mov_b64_e32 v[66:67], v[34:35]
	v_mov_b64_e32 v[70:71], v[34:35]
	v_mov_b64_e32 v[74:75], v[34:35]
	v_mov_b64_e32 v[78:79], v[34:35]
	v_mov_b64_e32 v[82:83], v[34:35]
	v_mov_b64_e32 v[86:87], v[34:35]
	v_mov_b64_e32 v[90:91], v[34:35]
	v_mov_b64_e32 v[94:95], v[34:35]
	v_mov_b64_e32 v[98:99], v[34:35]
	v_mov_b64_e32 v[102:103], v[34:35]
	v_mov_b64_e32 v[106:107], v[34:35]
	v_mov_b64_e32 v[110:111], v[34:35]
	v_mov_b64_e32 v[114:115], v[34:35]
	v_mov_b64_e32 v[118:119], v[34:35]
	v_mov_b64_e32 v[122:123], v[34:35]
	v_mov_b64_e32 v[126:127], v[34:35]
	v_mov_b64_e32 v[130:131], v[34:35]
	v_mov_b64_e32 v[42:43], v[34:35]
	v_mov_b64_e32 v[28:29], v[32:33]
	v_mov_b64_e32 v[20:21], v[32:33]
	v_mov_b64_e32 v[16:17], v[32:33]
	v_mov_b64_e32 v[12:13], v[32:33]
	v_mov_b64_e32 v[8:9], v[32:33]
	v_mov_b64_e32 v[4:5], v[32:33]
	v_mov_b64_e32 v[0:1], v[32:33]
	s_lshl_b64 s[6:7], s[6:7], 13
	v_lshl_add_u64 v[202:203], v[198:199], 0, s[0:1]
	s_and_b32 s15, s15, 0x1f0
	v_mov_b32_e32 v224, 0
	v_mov_b32_e32 v228, 0xff800000
	v_mov_b32_e32 v225, v219
	v_mov_b32_e32 v226, v221
	v_mov_b32_e32 v227, v220
	v_mov_b64_e32 v[26:27], v[34:35]
	v_mov_b64_e32 v[36:37], v[32:33]
	v_mov_b64_e32 v[44:45], v[32:33]
	v_mov_b64_e32 v[48:49], v[32:33]
	v_mov_b64_e32 v[52:53], v[32:33]
	v_mov_b64_e32 v[56:57], v[32:33]
	v_mov_b64_e32 v[60:61], v[32:33]
	v_mov_b64_e32 v[64:65], v[32:33]
	v_mov_b64_e32 v[68:69], v[32:33]
	v_mov_b64_e32 v[72:73], v[32:33]
	v_mov_b64_e32 v[76:77], v[32:33]
	v_mov_b64_e32 v[80:81], v[32:33]
	v_mov_b64_e32 v[84:85], v[32:33]
	v_mov_b64_e32 v[88:89], v[32:33]
	v_mov_b64_e32 v[92:93], v[32:33]
	v_mov_b64_e32 v[96:97], v[32:33]
	v_mov_b64_e32 v[100:101], v[32:33]
	v_mov_b64_e32 v[104:105], v[32:33]
	v_mov_b64_e32 v[108:109], v[32:33]
	v_mov_b64_e32 v[112:113], v[32:33]
	v_mov_b64_e32 v[116:117], v[32:33]
	v_mov_b64_e32 v[120:121], v[32:33]
	v_mov_b64_e32 v[124:125], v[32:33]
	v_mov_b64_e32 v[128:129], v[32:33]
	v_mov_b64_e32 v[40:41], v[32:33]
	v_mov_b64_e32 v[30:31], v[34:35]
	v_mov_b64_e32 v[22:23], v[34:35]
	v_mov_b64_e32 v[18:19], v[34:35]
	v_mov_b64_e32 v[14:15], v[34:35]
	v_mov_b64_e32 v[10:11], v[34:35]
	v_mov_b64_e32 v[6:7], v[34:35]
	v_mov_b64_e32 v[2:3], v[34:35]
	s_andn2_b64 vcc, exec, s[2:3]
	v_cmp_ge_u32_e64 s[0:1], s4, v225
	s_cbranch_vccnz .Lat_iv_a_p
	ds_read_b32 v32, v226
	s_branch .Lat_iv_b_p
.Lat_iv_a_p:
	s_nop 1
	v_cndmask_b32_e64 v32, 0, v225, s[0:1]
.Lat_iv_b_p:
	s_waitcnt lgkmcnt(0)
	s_mov_b32 s69, 0
	s_mov_b32 s71, 0
	s_mov_b32 s73, 0
	s_mov_b32 s75, 0
	s_mov_b32 s77, 0
	s_mov_b32 s79, 0
	s_mov_b32 s81, 0
	s_mov_b32 s83, 0
	s_mov_b32 s85, 0
	s_mov_b32 s89, 0
	s_mov_b32 s91, 0
	s_mov_b32 s93, 0
	s_mov_b32 s95, 0
	s_mov_b32 s97, 0
	s_mov_b32 s99, 0
	s_mov_b32 s35, 0
	v_readlane_b32 s68, v32, 0
	v_readlane_b32 s70, v32, 1
	v_readlane_b32 s72, v32, 2
	v_readlane_b32 s74, v32, 3
	v_readlane_b32 s76, v32, 4
	v_readlane_b32 s78, v32, 5
	v_readlane_b32 s80, v32, 6
	v_readlane_b32 s82, v32, 7
	v_readlane_b32 s84, v32, 8
	v_readlane_b32 s88, v32, 9
	v_readlane_b32 s90, v32, 10
	v_readlane_b32 s92, v32, 11
	v_readlane_b32 s94, v32, 12
	v_readlane_b32 s96, v32, 13
	v_readlane_b32 s98, v32, 14
	v_readlane_b32 s34, v32, 15
	s_lshl_b32 s68, s68, 10
	s_lshl_b32 s70, s70, 10
	s_lshl_b32 s72, s72, 10
	s_lshl_b32 s74, s74, 10
	s_lshl_b32 s76, s76, 10
	s_lshl_b32 s78, s78, 10
	s_lshl_b32 s80, s80, 10
	s_lshl_b32 s82, s82, 10
	s_lshl_b32 s84, s84, 10
	s_lshl_b32 s88, s88, 10
	s_lshl_b32 s90, s90, 10
	s_lshl_b32 s92, s92, 10
	s_lshl_b32 s94, s94, 10
	s_lshl_b32 s96, s96, 10
	s_lshl_b32 s98, s98, 10
	s_lshl_b32 s34, s34, 10
	s_waitcnt vmcnt(0)
	s_branch .LBB0_904
.LBB0_903:
	v_sub_f32_e32 v32, v34, v228
	v_sub_f32_e32 v34, v35, v228
	v_mul_f32_e32 v34, 0x3fb8aa3b, v34
	v_exp_f32_e32 v234, v34
	v_sub_f32_e32 v34, v229, v228
	v_mul_f32_e32 v34, 0x3fb8aa3b, v34
	v_exp_f32_e32 v229, v34
	v_sub_f32_e32 v34, v230, v228
	v_mul_f32_e32 v32, 0x3fb8aa3b, v32
	v_mul_f32_e32 v34, 0x3fb8aa3b, v34
	v_exp_f32_e32 v32, v32
	v_exp_f32_e32 v235, v34
	v_cvt_pk_bf16_f32 v230, v234, s0
	v_cvt_pk_bf16_f32 v35, v229, s0
	v_cvt_pk_bf16_f32 v34, v32, s0
	v_cvt_pk_bf16_f32 v231, v235, s0
	s_mov_b32 s0, 0x5040100
	v_perm_b32 v35, v231, v35, s0
	v_perm_b32 v34, v230, v34, s0
	v_add_f32_e32 v32, v224, v32
	v_add_f32_e32 v32, v234, v32
	v_add_f32_e32 v32, v229, v32
	v_add_f32_e32 v224, v235, v32
	v_add_u32_e32 v227, 16, v227
	v_add_u32_e32 v226, 64, v226
	v_add_u32_e32 v225, 16, v225
	s_andn2_b64 vcc, exec, s[2:3]
	v_cmp_ge_u32_e64 s[0:1], s4, v225
	s_cbranch_vccnz .Lat_iv_a_n
	ds_read_b32 v32, v226
	s_branch .Lat_iv_b_n

; #define LDSP(TY, p) ((__attribute__((address_space(3))) TY*)(p))
; #define WAIT_L0() asm volatile("s_waitcnt lgkmcnt(0)" ::: "memory")
; __device__ __forceinline__ void ph_attn(const Params& p, char* shm) {
;     ...
;       const int slot = c * 16 + hd;
;       int iv = (slot < cnt) ? slot : 0;
;       if (t >= 256) iv = idxl[slot];
;       WAIT_L0();
; #pragma unroll
;       for (int j = 0; j < 16; ++j) {
;         const int kidx = __builtin_amdgcn_readlane(iv, j);
;     ...
;       const s16x4 pb = {(short)f2bf(pj[0]), (short)f2bf(pj[1]), (short)f2bf(pj[2]), (short)f2bf(pj[3])};
; #pragma unroll
;       for (int dt = 0; dt < 32; ++dt) {
;         const s16x4 a = __builtin_amdgcn_ds_read_tr16_b64_v4i16(LDSP(s16x4, wb + rd + dt * 32));
;         O[dt] = __builtin_amdgcn_mfma_f32_16x16x16bf16_1k(a, pb, O[dt], 0, 0, 0);
;       }
.Lat_iv_b_n:
	ds_read_b64_tr_b16 v[230:231], v223
	ds_read_b64_tr_b16 v[232:233], v223 offset:32
	ds_read_b64_tr_b16 v[234:235], v223 offset:64
	ds_read_b64_tr_b16 v[236:237], v223 offset:96
	ds_read_b64_tr_b16 v[238:239], v223 offset:128
	ds_read_b64_tr_b16 v[240:241], v223 offset:160
	ds_read_b64_tr_b16 v[242:243], v223 offset:192
	s_waitcnt lgkmcnt(6)
	v_mfma_f32_16x16x16_bf16 v[128:131], v[230:231], v[34:35], v[128:131]
	v_readlane_b32 s68, v32, 0
	ds_read_b64_tr_b16 v[230:231], v223 offset:224
	s_waitcnt lgkmcnt(6)
	v_mfma_f32_16x16x16_bf16 v[124:127], v[232:233], v[34:35], v[124:127]
	v_readlane_b32 s70, v32, 1
	s_lshl_b32 s68, s68, 10
	ds_read_b64_tr_b16 v[232:233], v223 offset:256
	s_waitcnt lgkmcnt(6)
	v_mfma_f32_16x16x16_bf16 v[120:123], v[234:235], v[34:35], v[120:123]
	v_readlane_b32 s72, v32, 2
	s_lshl_b32 s70, s70, 10
	ds_read_b64_tr_b16 v[234:235], v223 offset:288
	s_waitcnt lgkmcnt(6)
	v_mfma_f32_16x16x16_bf16 v[116:119], v[236:237], v[34:35], v[116:119]
	v_readlane_b32 s74, v32, 3
	s_lshl_b32 s72, s72, 10
	ds_read_b64_tr_b16 v[236:237], v223 offset:320
	s_waitcnt lgkmcnt(6)
	v_mfma_f32_16x16x16_bf16 v[112:115], v[238:239], v[34:35], v[112:115]
	v_readlane_b32 s76, v32, 4
	s_lshl_b32 s74, s74, 10
	ds_read_b64_tr_b16 v[238:239], v223 offset:352
	s_waitcnt lgkmcnt(6)
	v_mfma_f32_16x16x16_bf16 v[108:111], v[240:241], v[34:35], v[108:111]
	v_readlane_b32 s78, v32, 5
	s_lshl_b32 s76, s76, 10
	ds_read_b64_tr_b16 v[240:241], v223 offset:384
	s_waitcnt lgkmcnt(6)
	v_mfma_f32_16x16x16_bf16 v[104:107], v[242:243], v[34:35], v[104:107]
	v_readlane_b32 s80, v32, 6
	s_lshl_b32 s78, s78, 10
	ds_read_b64_tr_b16 v[242:243], v223 offset:416
	s_waitcnt lgkmcnt(6)
	v_mfma_f32_16x16x16_bf16 v[100:103], v[230:231], v[34:35], v[100:103]
	v_readlane_b32 s82, v32, 7
	s_lshl_b32 s80, s80, 10
	ds_read_b64_tr_b16 v[230:231], v223 offset:448
	s_waitcnt lgkmcnt(6)
	v_mfma_f32_16x16x16_bf16 v[96:99], v[232:233], v[34:35], v[96:99]
	v_readlane_b32 s84, v32, 8
	s_lshl_b32 s82, s82, 10
	ds_read_b64_tr_b16 v[232:233], v223 offset:480
	s_waitcnt lgkmcnt(6)
	v_mfma_f32_16x16x16_bf16 v[92:95], v[234:235], v[34:35], v[92:95]
	v_readlane_b32 s88, v32, 9
	s_lshl_b32 s84, s84, 10
	ds_read_b64_tr_b16 v[234:235], v223 offset:512
	s_waitcnt lgkmcnt(6)
	v_mfma_f32_16x16x16_bf16 v[88:91], v[236:237], v[34:35], v[88:91]
	v_readlane_b32 s90, v32, 10
	s_lshl_b32 s88, s88, 10
	ds_read_b64_tr_b16 v[236:237], v223 offset:544
	s_waitcnt lgkmcnt(6)
	v_mfma_f32_16x16x16_bf16 v[84:87], v[238:239], v[34:35], v[84:87]
	v_readlane_b32 s92, v32, 11
	s_lshl_b32 s90, s90, 10
	ds_read_b64_tr_b16 v[238:239], v223 offset:576
	s_waitcnt lgkmcnt(6)
	v_mfma_f32_16x16x16_bf16 v[80:83], v[240:241], v[34:35], v[80:83]
	v_readlane_b32 s94, v32, 12
	s_lshl_b32 s92, s92, 10
	ds_read_b64_tr_b16 v[240:241], v223 offset:608
	s_waitcnt lgkmcnt(6)
	v_mfma_f32_16x16x16_bf16 v[76:79], v[242:243], v[34:35], v[76:79]
	v_readlane_b32 s96, v32, 13
	s_lshl_b32 s94, s94, 10
	ds_read_b64_tr_b16 v[242:243], v223 offset:640
	s_waitcnt lgkmcnt(6)
	v_mfma_f32_16x16x16_bf16 v[72:75], v[230:231], v[34:35], v[72:75]
	v_readlane_b32 s98, v32, 14
	s_lshl_b32 s96, s96, 10
	ds_read_b64_tr_b16 v[230:231], v223 offset:672
	s_waitcnt lgkmcnt(6)
	v_mfma_f32_16x16x16_bf16 v[68:71], v[232:233], v[34:35], v[68:71]
	v_readlane_b32 s34, v32, 15
	s_lshl_b32 s98, s98, 10
	ds_read_b64_tr_b16 v[232:233], v223 offset:704
	s_waitcnt lgkmcnt(6)
	v_mfma_f32_16x16x16_bf16 v[64:67], v[234:235], v[34:35], v[64:67]
	s_lshl_b32 s34, s34, 10
	ds_read_b64_tr_b16 v[234:235], v223 offset:736
	s_waitcnt lgkmcnt(6)
	v_mfma_f32_16x16x16_bf16 v[60:63], v[236:237], v[34:35], v[60:63]
	ds_read_b64_tr_b16 v[236:237], v223 offset:768
	s_waitcnt lgkmcnt(6)
	v_mfma_f32_16x16x16_bf16 v[56:59], v[238:239], v[34:35], v[56:59]
	ds_read_b64_tr_b16 v[238:239], v223 offset:800
	s_waitcnt lgkmcnt(6)
	v_mfma_f32_16x16x16_bf16 v[52:55], v[240:241], v[34:35], v[52:55]
	ds_read_b64_tr_b16 v[240:241], v223 offset:832
	s_waitcnt lgkmcnt(6)
	v_mfma_f32_16x16x16_bf16 v[48:51], v[242:243], v[34:35], v[48:51]
	ds_read_b64_tr_b16 v[242:243], v223 offset:864
	s_waitcnt lgkmcnt(6)
	v_mfma_f32_16x16x16_bf16 v[44:47], v[230:231], v[34:35], v[44:47]
	ds_read_b64_tr_b16 v[230:231], v223 offset:896
	s_waitcnt lgkmcnt(6)
	v_mfma_f32_16x16x16_bf16 v[36:39], v[232:233], v[34:35], v[36:39]
	ds_read_b64_tr_b16 v[232:233], v223 offset:928
	s_waitcnt lgkmcnt(6)
	v_mfma_f32_16x16x16_bf16 v[24:27], v[234:235], v[34:35], v[24:27]
	ds_read_b64_tr_b16 v[234:235], v223 offset:960
	s_waitcnt lgkmcnt(6)
	v_mfma_f32_16x16x16_bf16 v[40:43], v[236:237], v[34:35], v[40:43]
	ds_read_b64_tr_b16 v[236:237], v223 offset:992
	s_waitcnt lgkmcnt(6)
	v_mfma_f32_16x16x16_bf16 v[28:31], v[238:239], v[34:35], v[28:31]
	s_waitcnt lgkmcnt(5)
	v_mfma_f32_16x16x16_bf16 v[20:23], v[240:241], v[34:35], v[20:23]
	s_waitcnt lgkmcnt(4)
	v_mfma_f32_16x16x16_bf16 v[16:19], v[242:243], v[34:35], v[16:19]
	s_waitcnt lgkmcnt(3)
	v_mfma_f32_16x16x16_bf16 v[12:15], v[230:231], v[34:35], v[12:15]
	s_waitcnt lgkmcnt(2)
	v_mfma_f32_16x16x16_bf16 v[8:11], v[232:233], v[34:35], v[8:11]
	s_waitcnt lgkmcnt(1)
	v_mfma_f32_16x16x16_bf16 v[4:7], v[234:235], v[34:35], v[4:7]
	s_waitcnt lgkmcnt(0)
	v_mfma_f32_16x16x16_bf16 v[0:3], v[236:237], v[34:35], v[0:3]
	s_add_i32 s15, s15, -16
	s_cmp_eq_u32 s15, 0
	s_cbranch_scc1 .LBB0_66
; #define LDSP(TY, p) ((__attribute__((address_space(3))) TY*)(p))
; #define WAIT_V0() asm volatile("s_waitcnt vmcnt(0)" ::: "memory")
; #define WAIT_L0() asm volatile("s_waitcnt lgkmcnt(0)" ::: "memory")
; __device__ __forceinline__ void ph_attn(const Params& p, char* shm) {
;     ...
;     for (int c = 0; c < nchunk; ++c) {
;       const int slot = c * 16 + hd;
;       int iv = (slot < cnt) ? slot : 0;
;       if (t >= 256) iv = idxl[slot];
;       WAIT_L0();
; #pragma unroll
;       for (int j = 0; j < 16; ++j) {
;         const int kidx = __builtin_amdgcn_readlane(iv, j);
;         __builtin_amdgcn_global_load_lds((const unsigned*)(ckvb + (size_t)kidx * 512 + lane * 8), LDSP(unsigned, wb + j * 1040), 16, 0, 0);
;       }
;       WAIT_V0();
;       f32x4 s = {0.f, 0.f, 0.f, 0.f};
; #pragma unroll
;       for (int ks = 0; ks < 16; ++ks) {
;         const s16x8 a = *(const s16x8*)(wb + hd * 1040 + ks * 64 + g4 * 16);
;         s = __builtin_amdgcn_mfma_f32_16x16x32_bf16(a, qb[ks], s, 0, 0, 0);
;       }
;       float sv[4], cmax = -INFINITY;
; #pragma unroll
;       for (int j = 0; j < 4; ++j) {
;         const int sl = c * 16 + g4 * 4 + j;
;         sv[j] = (sl < cnt) ? s[j] * scale : -INFINITY;
;         cmax = fmaxf(cmax, sv[j]);
;       }
;       {
;         auto r16 = __builtin_amdgcn_permlane16_swap(__float_as_uint(cmax), __float_as_uint(cmax), false, false);
;         cmax = fmaxf(__uint_as_float(r16[0]), __uint_as_float(r16[1]));
;         auto r32 = __builtin_amdgcn_permlane32_swap(__float_as_uint(cmax), __float_as_uint(cmax), false, false);
;         cmax = fmaxf(__uint_as_float(r32[0]), __uint_as_float(r32[1]));
;       }
;       if (__ballot(cmax > mref + 8.f)) {
.LBB0_904:
	s_mov_b32 m0, s8
	v_lshl_add_u64 v[34:35], v[202:203], 0, s[68:69]
	global_load_lds_dwordx4 v[34:35], off
	s_add_i32 m0, s8, 0x410
	v_lshl_add_u64 v[34:35], v[202:203], 0, s[70:71]
	global_load_lds_dwordx4 v[34:35], off
	s_add_i32 m0, s8, 0x820
	v_lshl_add_u64 v[34:35], v[202:203], 0, s[72:73]
	global_load_lds_dwordx4 v[34:35], off
	s_add_i32 m0, s8, 0xc30
	v_lshl_add_u64 v[34:35], v[202:203], 0, s[74:75]
	global_load_lds_dwordx4 v[34:35], off
	s_add_i32 m0, s8, 0x1040
	v_lshl_add_u64 v[34:35], v[202:203], 0, s[76:77]
	global_load_lds_dwordx4 v[34:35], off
	s_add_i32 m0, s8, 0x1450
	v_lshl_add_u64 v[34:35], v[202:203], 0, s[78:79]
	global_load_lds_dwordx4 v[34:35], off
	s_add_i32 m0, s8, 0x1860
	v_lshl_add_u64 v[34:35], v[202:203], 0, s[80:81]
	global_load_lds_dwordx4 v[34:35], off
	s_add_i32 m0, s8, 0x1c70
	v_lshl_add_u64 v[34:35], v[202:203], 0, s[82:83]
	global_load_lds_dwordx4 v[34:35], off
	s_add_i32 m0, s8, 0x2080
	v_lshl_add_u64 v[34:35], v[202:203], 0, s[84:85]
	global_load_lds_dwordx4 v[34:35], off
	s_add_i32 m0, s8, 0x2490
	v_lshl_add_u64 v[34:35], v[202:203], 0, s[88:89]
	global_load_lds_dwordx4 v[34:35], off
	s_add_i32 m0, s8, 0x28a0
	v_lshl_add_u64 v[34:35], v[202:203], 0, s[90:91]
	global_load_lds_dwordx4 v[34:35], off
	s_add_i32 m0, s8, 0x2cb0
	v_lshl_add_u64 v[34:35], v[202:203], 0, s[92:93]
	global_load_lds_dwordx4 v[34:35], off
	s_add_i32 m0, s8, 0x30c0
	v_lshl_add_u64 v[34:35], v[202:203], 0, s[94:95]
	global_load_lds_dwordx4 v[34:35], off
	s_add_i32 m0, s8, 0x34d0
	v_lshl_add_u64 v[34:35], v[202:203], 0, s[96:97]
	global_load_lds_dwordx4 v[34:35], off
	s_add_i32 m0, s8, 0x38e0
	v_lshl_add_u64 v[34:35], v[202:203], 0, s[98:99]
	global_load_lds_dwordx4 v[34:35], off
	s_add_i32 m0, s8, 0x3cf0
	v_lshl_add_u64 v[34:35], v[202:203], 0, s[34:35]
	global_load_lds_dwordx4 v[34:35], off
	v_cmp_ge_u32_e32 vcc, s4, v227
	s_waitcnt vmcnt(0)
	ds_read_b128 v[234:237], v222
	ds_read_b128 v[238:241], v222 offset:64
	v_add_u32_e32 v229, 2, v227
	s_mov_b32 s0, 0xff800000
	s_waitcnt lgkmcnt(1)
	v_mfma_f32_16x16x32_bf16 v[230:233], v[234:237], v[132:135], 0
	ds_read_b128 v[234:237], v222 offset:128
	s_waitcnt lgkmcnt(1)
	v_mfma_f32_16x16x32_bf16 v[230:233], v[238:241], v[136:139], v[230:233]
	ds_read_b128 v[238:241], v222 offset:192
	s_waitcnt lgkmcnt(1)
	v_mfma_f32_16x16x32_bf16 v[230:233], v[234:237], v[140:143], v[230:233]
	ds_read_b128 v[234:237], v222 offset:256
	s_waitcnt lgkmcnt(1)
	v_mfma_f32_16x16x32_bf16 v[230:233], v[238:241], v[144:147], v[230:233]
	ds_read_b128 v[238:241], v222 offset:320
	s_waitcnt lgkmcnt(1)
	v_mfma_f32_16x16x32_bf16 v[230:233], v[234:237], v[148:151], v[230:233]
	ds_read_b128 v[234:237], v222 offset:384
	s_waitcnt lgkmcnt(1)
	v_mfma_f32_16x16x32_bf16 v[230:233], v[238:241], v[152:155], v[230:233]
	ds_read_b128 v[238:241], v222 offset:448
	s_waitcnt lgkmcnt(1)
	v_mfma_f32_16x16x32_bf16 v[230:233], v[234:237], v[156:159], v[230:233]
	ds_read_b128 v[234:237], v222 offset:512
	s_waitcnt lgkmcnt(1)
	v_mfma_f32_16x16x32_bf16 v[230:233], v[238:241], v[160:163], v[230:233]
	ds_read_b128 v[238:241], v222 offset:576
	s_waitcnt lgkmcnt(1)
	v_mfma_f32_16x16x32_bf16 v[230:233], v[234:237], v[164:167], v[230:233]
	ds_read_b128 v[234:237], v222 offset:640
	s_waitcnt lgkmcnt(1)
	v_mfma_f32_16x16x32_bf16 v[230:233], v[238:241], v[168:171], v[230:233]
	ds_read_b128 v[238:241], v222 offset:704
	s_waitcnt lgkmcnt(1)
	v_mfma_f32_16x16x32_bf16 v[230:233], v[234:237], v[172:175], v[230:233]
	ds_read_b128 v[234:237], v222 offset:768
	s_waitcnt lgkmcnt(1)
	v_mfma_f32_16x16x32_bf16 v[230:233], v[238:241], v[176:179], v[230:233]
	ds_read_b128 v[238:241], v222 offset:832
	s_waitcnt lgkmcnt(1)
	v_mfma_f32_16x16x32_bf16 v[230:233], v[234:237], v[180:183], v[230:233]
	ds_read_b128 v[234:237], v222 offset:896
	s_waitcnt lgkmcnt(1)
	v_mfma_f32_16x16x32_bf16 v[230:233], v[238:241], v[184:187], v[230:233]
	ds_read_b128 v[238:241], v222 offset:960
	s_waitcnt lgkmcnt(1)
	v_mfma_f32_16x16x32_bf16 v[230:233], v[234:237], v[188:191], v[230:233]
	s_waitcnt lgkmcnt(0)
	v_mfma_f32_16x16x32_bf16 v[230:233], v[238:241], v[192:195], v[230:233]
	s_nop 7
	v_mul_f32_e32 v32, 0x3db504f3, v230
	v_cndmask_b32_e32 v34, v216, v32, vcc
	v_cmp_gt_u32_e32 vcc, s4, v227
	v_mul_f32_e32 v32, 0x3db504f3, v231
	v_mul_f32_e32 v230, 0x3db504f3, v232
	v_cndmask_b32_e32 v35, v216, v32, vcc
	v_cmp_ge_u32_e32 vcc, s4, v229
	v_mul_f32_e32 v231, 0x3db504f3, v233
	v_max3_f32 v32, v34, s0, v35
	v_cndmask_b32_e32 v229, v216, v230, vcc
	v_add_u32_e32 v230, 3, v227
	v_cmp_ge_u32_e32 vcc, s4, v230
	s_nop 1
	v_cndmask_b32_e32 v230, v216, v231, vcc
	v_max3_f32 v32, v32, v229, v230
	v_mov_b32_e32 v231, v32
	s_nop 1
	v_permlane16_swap_b32_e32 v32, v231
	v_max_f32_e32 v231, v231, v231
	v_max_f32_e32 v32, v32, v32
	v_max_f32_e32 v32, v32, v231
	v_mov_b32_e32 v231, v32
	s_nop 1
	v_permlane32_swap_b32_e32 v32, v231
	v_max_f32_e32 v231, v231, v231
	v_max_f32_e32 v32, v32, v32
	v_max_f32_e32 v32, v32, v231
	v_add_f32_e32 v231, 0x41000000, v228
	v_cmp_gt_f32_e32 vcc, v32, v231
	s_cbranch_vccz .LBB0_903
; __device__ __forceinline__ void ph_attn(const Params& p, char* shm) {
;     ...
;       if (__ballot(cmax > mref + 8.f)) {
;         const float mn = fmaxf(mref, cmax);
;         const float al = __expf(mref - mn);
; #pragma unroll
;         for (int dt = 0; dt < 32; ++dt) O[dt] *= al;
;         lsum *= al;
;         mref = mn;
;       }
	v_max_f32_e32 v32, v32, v32
	v_max_f32_e32 v231, v228, v228
	v_max_f32_e32 v231, v231, v32
	v_sub_f32_e32 v32, v228, v231
	v_mul_f32_e32 v32, 0x3fb8aa3b, v32
	v_exp_f32_e32 v32, v32
	v_mov_b32_e32 v228, v231
	v_pk_mul_f32 v[130:131], v[130:131], v[32:33] op_sel_hi:[1,0]
	v_pk_mul_f32 v[128:129], v[128:129], v[32:33] op_sel_hi:[1,0]
	v_pk_mul_f32 v[126:127], v[126:127], v[32:33] op_sel_hi:[1,0]
	v_pk_mul_f32 v[124:125], v[124:125], v[32:33] op_sel_hi:[1,0]
	v_pk_mul_f32 v[122:123], v[122:123], v[32:33] op_sel_hi:[1,0]
	v_pk_mul_f32 v[120:121], v[120:121], v[32:33] op_sel_hi:[1,0]
	v_pk_mul_f32 v[118:119], v[118:119], v[32:33] op_sel_hi:[1,0]
	v_pk_mul_f32 v[116:117], v[116:117], v[32:33] op_sel_hi:[1,0]
	v_pk_mul_f32 v[114:115], v[114:115], v[32:33] op_sel_hi:[1,0]
	v_pk_mul_f32 v[112:113], v[112:113], v[32:33] op_sel_hi:[1,0]
	v_pk_mul_f32 v[110:111], v[110:111], v[32:33] op_sel_hi:[1,0]
	v_pk_mul_f32 v[108:109], v[108:109], v[32:33] op_sel_hi:[1,0]
	v_pk_mul_f32 v[106:107], v[106:107], v[32:33] op_sel_hi:[1,0]
	v_pk_mul_f32 v[104:105], v[104:105], v[32:33] op_sel_hi:[1,0]
	v_pk_mul_f32 v[102:103], v[102:103], v[32:33] op_sel_hi:[1,0]
	v_pk_mul_f32 v[100:101], v[100:101], v[32:33] op_sel_hi:[1,0]
	v_pk_mul_f32 v[98:99], v[98:99], v[32:33] op_sel_hi:[1,0]
	v_pk_mul_f32 v[96:97], v[96:97], v[32:33] op_sel_hi:[1,0]
	v_pk_mul_f32 v[94:95], v[94:95], v[32:33] op_sel_hi:[1,0]
	v_pk_mul_f32 v[92:93], v[92:93], v[32:33] op_sel_hi:[1,0]
	v_pk_mul_f32 v[90:91], v[90:91], v[32:33] op_sel_hi:[1,0]
	v_pk_mul_f32 v[88:89], v[88:89], v[32:33] op_sel_hi:[1,0]
	v_pk_mul_f32 v[86:87], v[86:87], v[32:33] op_sel_hi:[1,0]
	v_pk_mul_f32 v[84:85], v[84:85], v[32:33] op_sel_hi:[1,0]
	v_pk_mul_f32 v[82:83], v[82:83], v[32:33] op_sel_hi:[1,0]
	v_pk_mul_f32 v[80:81], v[80:81], v[32:33] op_sel_hi:[1,0]
	v_pk_mul_f32 v[78:79], v[78:79], v[32:33] op_sel_hi:[1,0]
	v_pk_mul_f32 v[76:77], v[76:77], v[32:33] op_sel_hi:[1,0]
	v_pk_mul_f32 v[74:75], v[74:75], v[32:33] op_sel_hi:[1,0]
	v_pk_mul_f32 v[72:73], v[72:73], v[32:33] op_sel_hi:[1,0]
	v_pk_mul_f32 v[70:71], v[70:71], v[32:33] op_sel_hi:[1,0]
	v_pk_mul_f32 v[68:69], v[68:69], v[32:33] op_sel_hi:[1,0]
	v_pk_mul_f32 v[66:67], v[66:67], v[32:33] op_sel_hi:[1,0]
	v_pk_mul_f32 v[64:65], v[64:65], v[32:33] op_sel_hi:[1,0]
	v_pk_mul_f32 v[62:63], v[62:63], v[32:33] op_sel_hi:[1,0]
	v_pk_mul_f32 v[60:61], v[60:61], v[32:33] op_sel_hi:[1,0]
	v_pk_mul_f32 v[58:59], v[58:59], v[32:33] op_sel_hi:[1,0]
	v_pk_mul_f32 v[56:57], v[56:57], v[32:33] op_sel_hi:[1,0]
	v_pk_mul_f32 v[54:55], v[54:55], v[32:33] op_sel_hi:[1,0]
	v_pk_mul_f32 v[52:53], v[52:53], v[32:33] op_sel_hi:[1,0]
	v_pk_mul_f32 v[50:51], v[50:51], v[32:33] op_sel_hi:[1,0]
	v_pk_mul_f32 v[48:49], v[48:49], v[32:33] op_sel_hi:[1,0]
	v_pk_mul_f32 v[46:47], v[46:47], v[32:33] op_sel_hi:[1,0]
	v_pk_mul_f32 v[44:45], v[44:45], v[32:33] op_sel_hi:[1,0]
	v_pk_mul_f32 v[38:39], v[38:39], v[32:33] op_sel_hi:[1,0]
	v_pk_mul_f32 v[36:37], v[36:37], v[32:33] op_sel_hi:[1,0]
	v_pk_mul_f32 v[26:27], v[26:27], v[32:33] op_sel_hi:[1,0]
	v_pk_mul_f32 v[24:25], v[24:25], v[32:33] op_sel_hi:[1,0]
	v_pk_mul_f32 v[42:43], v[42:43], v[32:33] op_sel_hi:[1,0]
	v_pk_mul_f32 v[40:41], v[40:41], v[32:33] op_sel_hi:[1,0]
	v_pk_mul_f32 v[30:31], v[30:31], v[32:33] op_sel_hi:[1,0]
	v_pk_mul_f32 v[28:29], v[28:29], v[32:33] op_sel_hi:[1,0]
	v_pk_mul_f32 v[22:23], v[22:23], v[32:33] op_sel_hi:[1,0]
	v_pk_mul_f32 v[20:21], v[20:21], v[32:33] op_sel_hi:[1,0]
	v_pk_mul_f32 v[18:19], v[18:19], v[32:33] op_sel_hi:[1,0]
	v_pk_mul_f32 v[16:17], v[16:17], v[32:33] op_sel_hi:[1,0]
	v_pk_mul_f32 v[14:15], v[14:15], v[32:33] op_sel_hi:[1,0]
	v_pk_mul_f32 v[12:13], v[12:13], v[32:33] op_sel_hi:[1,0]
	v_pk_mul_f32 v[10:11], v[10:11], v[32:33] op_sel_hi:[1,0]
	v_pk_mul_f32 v[8:9], v[8:9], v[32:33] op_sel_hi:[1,0]
	v_pk_mul_f32 v[6:7], v[6:7], v[32:33] op_sel_hi:[1,0]
	v_pk_mul_f32 v[4:5], v[4:5], v[32:33] op_sel_hi:[1,0]
	v_pk_mul_f32 v[2:3], v[2:3], v[32:33] op_sel_hi:[1,0]
	v_pk_mul_f32 v[0:1], v[0:1], v[32:33] op_sel_hi:[1,0]
	v_mul_f32_e32 v224, v224, v32
	s_branch .LBB0_903
